# v19 + scan chunk loop: end-of-chunk block barrier removed (next chunk's staging writes touch only thread-private slots and a region the epilogue reads do not cover)
# speedup vs baseline: 1.0135x; 1.0098x over previous
.LBB0_484:
	s_waitcnt lgkmcnt(0)
	s_barrier
	ds_read_b64 v[20:21], v194 offset:28736
	ds_read_b32 v22, v163 offset:28672
	ds_read_b128 v[8:11], v171 offset:24576
	ds_read_b128 v[12:15], v171 offset:20480
	s_waitcnt lgkmcnt(3)
	v_lshlrev_b32_e32 v116, 16, v20
	v_and_b32_e32 v117, 0xffff0000, v20
	s_waitcnt lgkmcnt(1)
	v_add_f32_e32 v16, v8, v9
	v_add_f32_e32 v16, v16, v10
	v_add_f32_e32 v16, v16, v11
	v_lshlrev_b32_e32 v20, 16, v21
	v_and_b32_e32 v21, 0xffff0000, v21
	v_add_f32_dpp v16, v16, v16 row_ror:8 row_mask:0xf bank_mask:0xf bound_ctrl:1
	s_nop 1
	v_add_f32_dpp v16, v16, v16 row_ror:4 row_mask:0xf bank_mask:0xf bound_ctrl:1
	s_nop 1
	v_add_f32_dpp v16, v16, v16 row_ror:2 row_mask:0xf bank_mask:0xf bound_ctrl:1
	s_nop 1
	v_add_f32_dpp v16, v16, v16 row_ror:1 row_mask:0xf bank_mask:0xf bound_ctrl:1
	v_mul_f32_e32 v16, 0x3c800000, v16
	v_pk_add_f32 v[118:119], v[8:9], v[16:17] op_sel_hi:[1,0] neg_lo:[0,1] neg_hi:[0,1]
	v_pk_add_f32 v[210:211], v[10:11], v[16:17] op_sel_hi:[1,0] neg_lo:[0,1] neg_hi:[0,1]
	v_pk_mul_f32 v[8:9], v[118:119], v[118:119]
	v_pk_mul_f32 v[10:11], v[210:211], v[210:211]
	v_add_f32_e32 v8, v8, v9
	v_add_f32_e32 v8, v10, v8
	v_add_f32_e32 v8, v11, v8
	s_nop 1
	v_add_f32_dpp v8, v8, v8 row_ror:8 row_mask:0xf bank_mask:0xf bound_ctrl:1
	s_nop 1
	v_add_f32_dpp v8, v8, v8 row_ror:4 row_mask:0xf bank_mask:0xf bound_ctrl:1
	s_nop 1
	v_add_f32_dpp v8, v8, v8 row_ror:2 row_mask:0xf bank_mask:0xf bound_ctrl:1
	s_nop 1
	v_add_f32_dpp v8, v8, v8 row_ror:1 row_mask:0xf bank_mask:0xf bound_ctrl:1
	v_fmamk_f32 v8, v8, 0x3c800000, v202
	v_mul_f32_e32 v9, 0x4b800000, v8
	v_cmp_gt_f32_e32 vcc, s68, v8
	s_nop 1
	v_cndmask_b32_e32 v8, v8, v9, vcc
	v_rsq_f32_e32 v23, v8
	ds_read_b128 v[8:11], v205 offset:32320
	ds_read_b128 v[16:19], v205 offset:32576
	v_mul_f32_e32 v40, 0x45800000, v23
	v_cndmask_b32_e32 v40, v23, v40, vcc
	v_pk_mul_f32 v[118:119], v[118:119], v[40:41] op_sel_hi:[1,0]
	s_and_b64 vcc, exec, s[0:1]
	s_waitcnt lgkmcnt(0)
	v_pk_fma_f32 v[8:9], v[8:9], v[118:119], v[16:17]
	s_nop 0
	v_pk_fma_f32 v[8:9], v[12:13], v[22:23], v[8:9] op_sel_hi:[1,0,1]
	v_pk_mul_f32 v[12:13], v[210:211], v[40:41] op_sel_hi:[1,0]
	v_pk_mul_f32 v[8:9], v[8:9], v[116:117]
	v_pk_fma_f32 v[10:11], v[10:11], v[12:13], v[18:19]
	v_cvt_pk_bf16_f32 v8, v8, v9
	v_pk_fma_f32 v[10:11], v[14:15], v[22:23], v[10:11] op_sel_hi:[1,0,1]
	s_nop 0
	v_pk_mul_f32 v[10:11], v[10:11], v[20:21]
	s_nop 0
	v_cvt_pk_bf16_f32 v9, v10, v11
	v_lshl_add_u64 v[10:11], v[70:71], 0, s[28:29]
	v_lshlrev_b64 v[10:11], 11, v[10:11]
	v_lshl_add_u64 v[10:11], v[92:93], 0, v[10:11]
	s_mov_b32 s28, s62
	global_store_dwordx2 v[10:11], v[8:9], off
	s_nop 0
	s_cbranch_vccnz .LBB0_472
